# v6 plus P10 out-proj epilogue: all 32 bf16 residual loads issued before the stores
# speedup vs baseline: 1.0118x; 1.0035x over previous
; __device__ __forceinline__ float bflo(unsigned w) { return __uint_as_float(w << 16); }
; __device__ __forceinline__ float bfhi(unsigned w) { return __uint_as_float(w & 0xffff0000u); }
; __device__ __forceinline__ unsigned cvt_pk_bf16(float lo, float hi) { unsigned r; asm volatile("v_cvt_pk_bf16_f32 %0, %1, %2" : "=v"(r) : "v"(lo), "v"(hi)); return r; }
;     __device__ __forceinline__ void operator()(const f32x4 (&acc)[2][2][4][2], const Unit& u, int wr, int wc, int fr, int fq) const {
;         const int row0 = u.pm * BM + wr * 64 + fr, col0 = u.pn * BM + wc * 32 + 4 * fq;
;         const float* gv = gate + (size_t)((u.pm * BM) / SEQ) * 6144 + col0;
;         f32x4 g[2][2];
; #pragma unroll
;         for (int bj = 0; bj < 2; ++bj)
; #pragma unroll
;             for (int n = 0; n < 2; ++n) g[bj][n] = *(const f32x4*)(gv + bj * HALF + n * 16);
; #pragma unroll
;         for (int ai = 0; ai < 2; ++ai)
; #pragma unroll
;             for (int m = 0; m < 4; ++m) { const size_t off = (size_t)(row0 + ai * HALF + m * 16) * 2048 + col0;
; #pragma unroll
;                 for (int bj = 0; bj < 2; ++bj)
; #pragma unroll
;                     for (int n = 0; n < 2; ++n) { const u32x2 bw = *(const u32x2*)(base + off + bj * HALF + n * 16);
;                         const f32x4 b = {bflo(bw.x), bfhi(bw.x), bflo(bw.y), bfhi(bw.y)}; const f32x4 o = b + g[bj][n] * acc[ai][bj][m][n];
;                         u32x2 w; w.x = cvt_pk_bf16(o[0], o[1]); w.y = cvt_pk_bf16(o[2], o[3]); *(u32x2*)(out + off + bj * HALF + n * 16) = w; } }
;     }
.LBB0_1076:
	s_ashr_i32 s21, s28, 31
	s_lshr_b32 s21, s21, 27
	v_lshl_add_u32 v160, s28, 8, v162
	v_lshl_or_b32 v158, s53, 8, v164
	s_add_i32 s21, s28, s21
	v_ashrrev_i32_e32 v161, 31, v160
	s_ashr_i32 s21, s21, 5
	v_ashrrev_i32_e32 v159, 31, v158
	v_lshlrev_b64 v[116:117], 11, v[160:161]
	s_mul_hi_i32 s23, s21, 0x6000
	s_mulk_i32 s21, 0x6000
	v_lshl_add_u64 v[116:117], v[116:117], 0, v[158:159]
	v_lshlrev_b64 v[156:157], 1, v[116:117]
	s_add_u32 s30, s45, s21
	s_addc_u32 s31, s46, s23
	v_lshl_add_u64 v[116:117], v[158:159], 2, s[30:31]
	global_load_dwordx4 v[128:131], v[116:117], off
	global_load_dwordx4 v[132:135], v[116:117], off offset:64
	global_load_dwordx4 v[124:127], v[116:117], off offset:512
	s_nop 0
	global_load_dwordx4 v[116:119], v[116:117], off offset:576
	s_andn2_b64 vcc, exec, s[2:3]
	s_mov_b64 s[2:3], -1
	v_or_b32_e32 v214, 16, v160
	v_ashrrev_i32_e32 v215, 31, v214
	v_lshlrev_b64 v[214:215], 11, v[214:215]
	v_lshl_add_u64 v[214:215], v[214:215], 0, v[158:159]
	v_lshlrev_b64 v[214:215], 1, v[214:215]
	v_or_b32_e32 v216, 32, v160
	v_ashrrev_i32_e32 v217, 31, v216
	v_lshlrev_b64 v[216:217], 11, v[216:217]
	v_lshl_add_u64 v[216:217], v[216:217], 0, v[158:159]
	v_lshlrev_b64 v[216:217], 1, v[216:217]
	v_or_b32_e32 v218, 48, v160
	v_ashrrev_i32_e32 v219, 31, v218
	v_lshlrev_b64 v[218:219], 11, v[218:219]
	v_lshl_add_u64 v[218:219], v[218:219], 0, v[158:159]
	v_lshlrev_b64 v[218:219], 1, v[218:219]
	v_lshl_add_u64 v[220:221], v[156:157], 0, s[4:5]
	v_lshl_add_u64 v[172:173], v[156:157], 0, s[14:15]
	v_lshl_add_u64 v[174:175], v[156:157], 0, s[16:17]
	v_lshl_add_u64 v[176:177], v[156:157], 0, s[18:19]
	v_lshl_add_u64 v[170:171], s[88:89], 0, v[156:157]
	global_load_dwordx2 v[178:179], v[170:171], off
	global_load_dwordx2 v[180:181], v[170:171], off offset:32
	global_load_dwordx2 v[182:183], v[170:171], off offset:256
	global_load_dwordx2 v[184:185], v[170:171], off offset:288
	v_lshl_add_u64 v[170:171], s[88:89], 0, v[214:215]
	global_load_dwordx2 v[186:187], v[170:171], off
	global_load_dwordx2 v[188:189], v[170:171], off offset:32
	global_load_dwordx2 v[190:191], v[170:171], off offset:256
	global_load_dwordx2 v[192:193], v[170:171], off offset:288
	v_lshl_add_u64 v[170:171], s[88:89], 0, v[216:217]
	global_load_dwordx2 v[194:195], v[170:171], off
	global_load_dwordx2 v[196:197], v[170:171], off offset:32
	global_load_dwordx2 v[198:199], v[170:171], off offset:256
	global_load_dwordx2 v[200:201], v[170:171], off offset:288
	v_lshl_add_u64 v[170:171], s[88:89], 0, v[218:219]
	global_load_dwordx2 v[202:203], v[170:171], off
	global_load_dwordx2 v[204:205], v[170:171], off offset:32
	global_load_dwordx2 v[206:207], v[170:171], off offset:256
	global_load_dwordx2 v[208:209], v[170:171], off offset:288
	v_lshl_add_u64 v[170:171], s[88:89], 0, v[220:221]
	global_load_dwordx2 v[210:211], v[170:171], off
	global_load_dwordx2 v[212:213], v[170:171], off offset:32
	global_load_dwordx2 v[222:223], v[170:171], off offset:256
	global_load_dwordx2 v[224:225], v[170:171], off offset:288
	v_lshl_add_u64 v[170:171], s[88:89], 0, v[172:173]
	global_load_dwordx2 v[226:227], v[170:171], off
	global_load_dwordx2 v[228:229], v[170:171], off offset:32
	global_load_dwordx2 v[230:231], v[170:171], off offset:256
	global_load_dwordx2 v[232:233], v[170:171], off offset:288
	v_lshl_add_u64 v[170:171], s[88:89], 0, v[174:175]
	global_load_dwordx2 v[234:235], v[170:171], off
	global_load_dwordx2 v[236:237], v[170:171], off offset:32
	global_load_dwordx2 v[238:239], v[170:171], off offset:256
	global_load_dwordx2 v[240:241], v[170:171], off offset:288
	v_lshl_add_u64 v[170:171], s[88:89], 0, v[176:177]
	global_load_dwordx2 v[242:243], v[170:171], off
	global_load_dwordx2 v[244:245], v[170:171], off offset:32
	global_load_dwordx2 v[246:247], v[170:171], off offset:256
	global_load_dwordx2 v[248:249], v[170:171], off offset:288
	s_waitcnt vmcnt(31)
	v_lshl_add_u64 v[158:159], s[8:9], 0, v[156:157]
	v_lshlrev_b32_e32 v250, 16, v178
	v_and_b32_e32 v251, 0xffff0000, v178
	v_lshlrev_b32_e32 v252, 16, v179
	v_and_b32_e32 v253, 0xffff0000, v179
	v_pk_fma_f32 v[140:141], v[140:141], v[128:129], v[250:251]
	v_pk_fma_f32 v[142:143], v[142:143], v[130:131], v[252:253]
	v_cvt_pk_bf16_f32 v140, v140, v141
	s_nop 0
	v_cvt_pk_bf16_f32 v141, v142, v143
	global_store_dwordx2 v[158:159], v[140:141], off
	s_waitcnt vmcnt(31)
	v_lshlrev_b32_e32 v250, 16, v180
	v_and_b32_e32 v251, 0xffff0000, v180
	v_lshlrev_b32_e32 v252, 16, v181
	v_and_b32_e32 v253, 0xffff0000, v181
	v_pk_fma_f32 v[136:137], v[136:137], v[132:133], v[250:251]
	v_pk_fma_f32 v[138:139], v[138:139], v[134:135], v[252:253]
	v_cvt_pk_bf16_f32 v136, v136, v137
	s_nop 0
	v_cvt_pk_bf16_f32 v137, v138, v139
	global_store_dwordx2 v[158:159], v[136:137], off offset:32
	s_waitcnt vmcnt(31)
	v_lshlrev_b32_e32 v250, 16, v182
	v_and_b32_e32 v251, 0xffff0000, v182
	v_lshlrev_b32_e32 v252, 16, v183
	v_and_b32_e32 v253, 0xffff0000, v183
	v_pk_fma_f32 v[120:121], v[120:121], v[124:125], v[250:251]
	v_pk_fma_f32 v[122:123], v[122:123], v[126:127], v[252:253]
	v_cvt_pk_bf16_f32 v120, v120, v121
	s_nop 0
	v_cvt_pk_bf16_f32 v121, v122, v123
	global_store_dwordx2 v[158:159], v[120:121], off offset:256
	s_waitcnt vmcnt(31)
	v_lshlrev_b32_e32 v250, 16, v184
	v_and_b32_e32 v251, 0xffff0000, v184
	v_lshlrev_b32_e32 v252, 16, v185
	v_and_b32_e32 v253, 0xffff0000, v185
	v_pk_fma_f32 v[112:113], v[112:113], v[116:117], v[250:251]
	v_pk_fma_f32 v[114:115], v[114:115], v[118:119], v[252:253]
	v_cvt_pk_bf16_f32 v112, v112, v113
	s_nop 0
	v_cvt_pk_bf16_f32 v113, v114, v115
	global_store_dwordx2 v[158:159], v[112:113], off offset:288
	s_waitcnt vmcnt(31)
; __device__ __forceinline__ float bflo(unsigned w) { return __uint_as_float(w << 16); }
; __device__ __forceinline__ float bfhi(unsigned w) { return __uint_as_float(w & 0xffff0000u); }
; __device__ __forceinline__ unsigned cvt_pk_bf16(float lo, float hi) { unsigned r; asm volatile("v_cvt_pk_bf16_f32 %0, %1, %2" : "=v"(r) : "v"(lo), "v"(hi)); return r; }
;     __device__ __forceinline__ void operator()(const f32x4 (&acc)[2][2][4][2], const Unit& u, int wr, int wc, int fr, int fq) const {
;     ...
;         for (int ai = 0; ai < 2; ++ai)
; #pragma unroll
;             for (int m = 0; m < 4; ++m) { const size_t off = (size_t)(row0 + ai * HALF + m * 16) * 2048 + col0;
; #pragma unroll
;                 for (int bj = 0; bj < 2; ++bj)
; #pragma unroll
;                     for (int n = 0; n < 2; ++n) { const u32x2 bw = *(const u32x2*)(base + off + bj * HALF + n * 16);
;                         const f32x4 b = {bflo(bw.x), bfhi(bw.x), bflo(bw.y), bfhi(bw.y)}; const f32x4 o = b + g[bj][n] * acc[ai][bj][m][n];
;                         u32x2 w; w.x = cvt_pk_bf16(o[0], o[1]); w.y = cvt_pk_bf16(o[2], o[3]); *(u32x2*)(out + off + bj * HALF + n * 16) = w; } }
	v_lshl_add_u64 v[158:159], s[8:9], 0, v[214:215]
	v_lshlrev_b32_e32 v250, 16, v186
	v_and_b32_e32 v251, 0xffff0000, v186
	v_lshlrev_b32_e32 v252, 16, v187
	v_and_b32_e32 v253, 0xffff0000, v187
	v_pk_fma_f32 v[108:109], v[108:109], v[128:129], v[250:251]
	v_pk_fma_f32 v[110:111], v[110:111], v[130:131], v[252:253]
	v_cvt_pk_bf16_f32 v108, v108, v109
	s_nop 0
	v_cvt_pk_bf16_f32 v109, v110, v111
	global_store_dwordx2 v[158:159], v[108:109], off
	s_waitcnt vmcnt(31)
	v_lshlrev_b32_e32 v250, 16, v188
	v_and_b32_e32 v251, 0xffff0000, v188
	v_lshlrev_b32_e32 v252, 16, v189
	v_and_b32_e32 v253, 0xffff0000, v189
	v_pk_fma_f32 v[104:105], v[104:105], v[132:133], v[250:251]
	v_pk_fma_f32 v[106:107], v[106:107], v[134:135], v[252:253]
	v_cvt_pk_bf16_f32 v104, v104, v105
	s_nop 0
	v_cvt_pk_bf16_f32 v105, v106, v107
	global_store_dwordx2 v[158:159], v[104:105], off offset:32
	s_waitcnt vmcnt(31)
	v_lshlrev_b32_e32 v250, 16, v190
	v_and_b32_e32 v251, 0xffff0000, v190
	v_lshlrev_b32_e32 v252, 16, v191
	v_and_b32_e32 v253, 0xffff0000, v191
	v_pk_fma_f32 v[100:101], v[100:101], v[124:125], v[250:251]
	v_pk_fma_f32 v[102:103], v[102:103], v[126:127], v[252:253]
	v_cvt_pk_bf16_f32 v100, v100, v101
	s_nop 0
	v_cvt_pk_bf16_f32 v101, v102, v103
	global_store_dwordx2 v[158:159], v[100:101], off offset:256
	s_waitcnt vmcnt(31)
	v_lshlrev_b32_e32 v250, 16, v192
	v_and_b32_e32 v251, 0xffff0000, v192
	v_lshlrev_b32_e32 v252, 16, v193
	v_and_b32_e32 v253, 0xffff0000, v193
	v_pk_fma_f32 v[96:97], v[96:97], v[116:117], v[250:251]
	v_pk_fma_f32 v[98:99], v[98:99], v[118:119], v[252:253]
	v_cvt_pk_bf16_f32 v96, v96, v97
	s_nop 0
	v_cvt_pk_bf16_f32 v97, v98, v99
	global_store_dwordx2 v[158:159], v[96:97], off offset:288
	s_waitcnt vmcnt(31)
	v_lshl_add_u64 v[158:159], s[8:9], 0, v[216:217]
	v_lshlrev_b32_e32 v250, 16, v194
	v_and_b32_e32 v251, 0xffff0000, v194
	v_lshlrev_b32_e32 v252, 16, v195
	v_and_b32_e32 v253, 0xffff0000, v195
	v_pk_fma_f32 v[92:93], v[92:93], v[128:129], v[250:251]
	v_pk_fma_f32 v[94:95], v[94:95], v[130:131], v[252:253]
	v_cvt_pk_bf16_f32 v92, v92, v93
	s_nop 0
	v_cvt_pk_bf16_f32 v93, v94, v95
	global_store_dwordx2 v[158:159], v[92:93], off
	s_waitcnt vmcnt(31)
	v_lshlrev_b32_e32 v250, 16, v196
	v_and_b32_e32 v251, 0xffff0000, v196
	v_lshlrev_b32_e32 v252, 16, v197
	v_and_b32_e32 v253, 0xffff0000, v197
	v_pk_fma_f32 v[88:89], v[88:89], v[132:133], v[250:251]
	v_pk_fma_f32 v[90:91], v[90:91], v[134:135], v[252:253]
	v_cvt_pk_bf16_f32 v88, v88, v89
	s_nop 0
	v_cvt_pk_bf16_f32 v89, v90, v91
	global_store_dwordx2 v[158:159], v[88:89], off offset:32
	s_waitcnt vmcnt(31)
	v_lshlrev_b32_e32 v250, 16, v198
	v_and_b32_e32 v251, 0xffff0000, v198
	v_lshlrev_b32_e32 v252, 16, v199
	v_and_b32_e32 v253, 0xffff0000, v199
	v_pk_fma_f32 v[84:85], v[84:85], v[124:125], v[250:251]
	v_pk_fma_f32 v[86:87], v[86:87], v[126:127], v[252:253]
	v_cvt_pk_bf16_f32 v84, v84, v85
	s_nop 0
	v_cvt_pk_bf16_f32 v85, v86, v87
	global_store_dwordx2 v[158:159], v[84:85], off offset:256
	s_waitcnt vmcnt(31)
	v_lshlrev_b32_e32 v250, 16, v200
	v_and_b32_e32 v251, 0xffff0000, v200
	v_lshlrev_b32_e32 v252, 16, v201
	v_and_b32_e32 v253, 0xffff0000, v201
	v_pk_fma_f32 v[80:81], v[80:81], v[116:117], v[250:251]
	v_pk_fma_f32 v[82:83], v[82:83], v[118:119], v[252:253]
	v_cvt_pk_bf16_f32 v80, v80, v81
	s_nop 0
	v_cvt_pk_bf16_f32 v81, v82, v83
	global_store_dwordx2 v[158:159], v[80:81], off offset:288
	s_waitcnt vmcnt(31)
	v_lshl_add_u64 v[158:159], s[8:9], 0, v[218:219]
	v_lshlrev_b32_e32 v250, 16, v202
	v_and_b32_e32 v251, 0xffff0000, v202
	v_lshlrev_b32_e32 v252, 16, v203
	v_and_b32_e32 v253, 0xffff0000, v203
	v_pk_fma_f32 v[76:77], v[76:77], v[128:129], v[250:251]
	v_pk_fma_f32 v[78:79], v[78:79], v[130:131], v[252:253]
	v_cvt_pk_bf16_f32 v76, v76, v77
	s_nop 0
	v_cvt_pk_bf16_f32 v77, v78, v79
	global_store_dwordx2 v[158:159], v[76:77], off
	s_waitcnt vmcnt(31)
	v_lshlrev_b32_e32 v250, 16, v204
	v_and_b32_e32 v251, 0xffff0000, v204
	v_lshlrev_b32_e32 v252, 16, v205
	v_and_b32_e32 v253, 0xffff0000, v205
	v_pk_fma_f32 v[72:73], v[72:73], v[132:133], v[250:251]
	v_pk_fma_f32 v[74:75], v[74:75], v[134:135], v[252:253]
	v_cvt_pk_bf16_f32 v72, v72, v73
	s_nop 0
	v_cvt_pk_bf16_f32 v73, v74, v75
	global_store_dwordx2 v[158:159], v[72:73], off offset:32
	s_waitcnt vmcnt(31)
	v_lshlrev_b32_e32 v250, 16, v206
	v_and_b32_e32 v251, 0xffff0000, v206
	v_lshlrev_b32_e32 v252, 16, v207
	v_and_b32_e32 v253, 0xffff0000, v207
	v_pk_fma_f32 v[68:69], v[68:69], v[124:125], v[250:251]
	v_pk_fma_f32 v[70:71], v[70:71], v[126:127], v[252:253]
	v_cvt_pk_bf16_f32 v68, v68, v69
	s_nop 0
	v_cvt_pk_bf16_f32 v69, v70, v71
	global_store_dwordx2 v[158:159], v[68:69], off offset:256
	s_waitcnt vmcnt(31)
	v_lshlrev_b32_e32 v250, 16, v208
	v_and_b32_e32 v251, 0xffff0000, v208
	v_lshlrev_b32_e32 v252, 16, v209
	v_and_b32_e32 v253, 0xffff0000, v209
	v_pk_fma_f32 v[64:65], v[64:65], v[116:117], v[250:251]
	v_pk_fma_f32 v[66:67], v[66:67], v[118:119], v[252:253]
	v_cvt_pk_bf16_f32 v64, v64, v65
	s_nop 0
	v_cvt_pk_bf16_f32 v65, v66, v67
	global_store_dwordx2 v[158:159], v[64:65], off offset:288
	s_waitcnt vmcnt(31)
	v_lshl_add_u64 v[158:159], s[8:9], 0, v[220:221]
	v_lshlrev_b32_e32 v250, 16, v210
	v_and_b32_e32 v251, 0xffff0000, v210
	v_lshlrev_b32_e32 v252, 16, v211
	v_and_b32_e32 v253, 0xffff0000, v211
	v_pk_fma_f32 v[60:61], v[60:61], v[128:129], v[250:251]
	v_pk_fma_f32 v[62:63], v[62:63], v[130:131], v[252:253]
	v_cvt_pk_bf16_f32 v60, v60, v61
	s_nop 0
	v_cvt_pk_bf16_f32 v61, v62, v63
	global_store_dwordx2 v[158:159], v[60:61], off
	s_waitcnt vmcnt(31)
; __device__ __forceinline__ float bflo(unsigned w) { return __uint_as_float(w << 16); }
; __device__ __forceinline__ float bfhi(unsigned w) { return __uint_as_float(w & 0xffff0000u); }
; __device__ __forceinline__ unsigned cvt_pk_bf16(float lo, float hi) { unsigned r; asm volatile("v_cvt_pk_bf16_f32 %0, %1, %2" : "=v"(r) : "v"(lo), "v"(hi)); return r; }
;     __device__ __forceinline__ void operator()(const f32x4 (&acc)[2][2][4][2], const Unit& u, int wr, int wc, int fr, int fq) const {
;     ...
;         for (int ai = 0; ai < 2; ++ai)
; #pragma unroll
;             for (int m = 0; m < 4; ++m) { const size_t off = (size_t)(row0 + ai * HALF + m * 16) * 2048 + col0;
; #pragma unroll
;                 for (int bj = 0; bj < 2; ++bj)
; #pragma unroll
;                     for (int n = 0; n < 2; ++n) { const u32x2 bw = *(const u32x2*)(base + off + bj * HALF + n * 16);
;                         const f32x4 b = {bflo(bw.x), bfhi(bw.x), bflo(bw.y), bfhi(bw.y)}; const f32x4 o = b + g[bj][n] * acc[ai][bj][m][n];
;                         u32x2 w; w.x = cvt_pk_bf16(o[0], o[1]); w.y = cvt_pk_bf16(o[2], o[3]); *(u32x2*)(out + off + bj * HALF + n * 16) = w; } }
	v_lshlrev_b32_e32 v250, 16, v212
	v_and_b32_e32 v251, 0xffff0000, v212
	v_lshlrev_b32_e32 v252, 16, v213
	v_and_b32_e32 v253, 0xffff0000, v213
	v_pk_fma_f32 v[56:57], v[56:57], v[132:133], v[250:251]
	v_pk_fma_f32 v[58:59], v[58:59], v[134:135], v[252:253]
	v_cvt_pk_bf16_f32 v56, v56, v57
	s_nop 0
	v_cvt_pk_bf16_f32 v57, v58, v59
	global_store_dwordx2 v[158:159], v[56:57], off offset:32
	s_waitcnt vmcnt(31)
	v_lshlrev_b32_e32 v250, 16, v222
	v_and_b32_e32 v251, 0xffff0000, v222
	v_lshlrev_b32_e32 v252, 16, v223
	v_and_b32_e32 v253, 0xffff0000, v223
	v_pk_fma_f32 v[52:53], v[52:53], v[124:125], v[250:251]
	v_pk_fma_f32 v[54:55], v[54:55], v[126:127], v[252:253]
	v_cvt_pk_bf16_f32 v52, v52, v53
	s_nop 0
	v_cvt_pk_bf16_f32 v53, v54, v55
	global_store_dwordx2 v[158:159], v[52:53], off offset:256
	s_waitcnt vmcnt(31)
	v_lshlrev_b32_e32 v250, 16, v224
	v_and_b32_e32 v251, 0xffff0000, v224
	v_lshlrev_b32_e32 v252, 16, v225
	v_and_b32_e32 v253, 0xffff0000, v225
	v_pk_fma_f32 v[48:49], v[48:49], v[116:117], v[250:251]
	v_pk_fma_f32 v[50:51], v[50:51], v[118:119], v[252:253]
	v_cvt_pk_bf16_f32 v48, v48, v49
	s_nop 0
	v_cvt_pk_bf16_f32 v49, v50, v51
	global_store_dwordx2 v[158:159], v[48:49], off offset:288
	s_waitcnt vmcnt(31)
	v_lshl_add_u64 v[158:159], s[8:9], 0, v[172:173]
	v_lshlrev_b32_e32 v250, 16, v226
	v_and_b32_e32 v251, 0xffff0000, v226
	v_lshlrev_b32_e32 v252, 16, v227
	v_and_b32_e32 v253, 0xffff0000, v227
	v_pk_fma_f32 v[44:45], v[44:45], v[128:129], v[250:251]
	v_pk_fma_f32 v[46:47], v[46:47], v[130:131], v[252:253]
	v_cvt_pk_bf16_f32 v44, v44, v45
	s_nop 0
	v_cvt_pk_bf16_f32 v45, v46, v47
	global_store_dwordx2 v[158:159], v[44:45], off
	s_waitcnt vmcnt(31)
	v_lshlrev_b32_e32 v250, 16, v228
	v_and_b32_e32 v251, 0xffff0000, v228
	v_lshlrev_b32_e32 v252, 16, v229
	v_and_b32_e32 v253, 0xffff0000, v229
	v_pk_fma_f32 v[40:41], v[40:41], v[132:133], v[250:251]
	v_pk_fma_f32 v[42:43], v[42:43], v[134:135], v[252:253]
	v_cvt_pk_bf16_f32 v40, v40, v41
	s_nop 0
	v_cvt_pk_bf16_f32 v41, v42, v43
	global_store_dwordx2 v[158:159], v[40:41], off offset:32
	s_waitcnt vmcnt(31)
	v_lshlrev_b32_e32 v250, 16, v230
	v_and_b32_e32 v251, 0xffff0000, v230
	v_lshlrev_b32_e32 v252, 16, v231
	v_and_b32_e32 v253, 0xffff0000, v231
	v_pk_fma_f32 v[36:37], v[36:37], v[124:125], v[250:251]
	v_pk_fma_f32 v[38:39], v[38:39], v[126:127], v[252:253]
	v_cvt_pk_bf16_f32 v36, v36, v37
	s_nop 0
	v_cvt_pk_bf16_f32 v37, v38, v39
	global_store_dwordx2 v[158:159], v[36:37], off offset:256
	s_waitcnt vmcnt(31)
	v_lshlrev_b32_e32 v250, 16, v232
	v_and_b32_e32 v251, 0xffff0000, v232
	v_lshlrev_b32_e32 v252, 16, v233
	v_and_b32_e32 v253, 0xffff0000, v233
	v_pk_fma_f32 v[32:33], v[32:33], v[116:117], v[250:251]
	v_pk_fma_f32 v[34:35], v[34:35], v[118:119], v[252:253]
	v_cvt_pk_bf16_f32 v32, v32, v33
	s_nop 0
	v_cvt_pk_bf16_f32 v33, v34, v35
	global_store_dwordx2 v[158:159], v[32:33], off offset:288
	s_waitcnt vmcnt(31)
	v_lshl_add_u64 v[158:159], s[8:9], 0, v[174:175]
	v_lshlrev_b32_e32 v250, 16, v234
	v_and_b32_e32 v251, 0xffff0000, v234
	v_lshlrev_b32_e32 v252, 16, v235
	v_and_b32_e32 v253, 0xffff0000, v235
	v_pk_fma_f32 v[28:29], v[28:29], v[128:129], v[250:251]
	v_pk_fma_f32 v[30:31], v[30:31], v[130:131], v[252:253]
	v_cvt_pk_bf16_f32 v28, v28, v29
	s_nop 0
	v_cvt_pk_bf16_f32 v29, v30, v31
	global_store_dwordx2 v[158:159], v[28:29], off
	s_waitcnt vmcnt(31)
	v_lshlrev_b32_e32 v250, 16, v236
	v_and_b32_e32 v251, 0xffff0000, v236
	v_lshlrev_b32_e32 v252, 16, v237
	v_and_b32_e32 v253, 0xffff0000, v237
	v_pk_fma_f32 v[24:25], v[24:25], v[132:133], v[250:251]
	v_pk_fma_f32 v[26:27], v[26:27], v[134:135], v[252:253]
	v_cvt_pk_bf16_f32 v24, v24, v25
	s_nop 0
	v_cvt_pk_bf16_f32 v25, v26, v27
	global_store_dwordx2 v[158:159], v[24:25], off offset:32
	s_waitcnt vmcnt(31)
	v_lshlrev_b32_e32 v250, 16, v238
	v_and_b32_e32 v251, 0xffff0000, v238
	v_lshlrev_b32_e32 v252, 16, v239
	v_and_b32_e32 v253, 0xffff0000, v239
	v_pk_fma_f32 v[20:21], v[20:21], v[124:125], v[250:251]
	v_pk_fma_f32 v[22:23], v[22:23], v[126:127], v[252:253]
	v_cvt_pk_bf16_f32 v20, v20, v21
	s_nop 0
	v_cvt_pk_bf16_f32 v21, v22, v23
	global_store_dwordx2 v[158:159], v[20:21], off offset:256
	s_waitcnt vmcnt(31)
	v_lshlrev_b32_e32 v250, 16, v240
	v_and_b32_e32 v251, 0xffff0000, v240
	v_lshlrev_b32_e32 v252, 16, v241
	v_and_b32_e32 v253, 0xffff0000, v241
	v_pk_fma_f32 v[16:17], v[16:17], v[116:117], v[250:251]
	v_pk_fma_f32 v[18:19], v[18:19], v[118:119], v[252:253]
	v_cvt_pk_bf16_f32 v16, v16, v17
	s_nop 0
	v_cvt_pk_bf16_f32 v17, v18, v19
	global_store_dwordx2 v[158:159], v[16:17], off offset:288
	s_waitcnt vmcnt(31)
	v_lshl_add_u64 v[158:159], s[8:9], 0, v[176:177]
	v_lshlrev_b32_e32 v250, 16, v242
	v_and_b32_e32 v251, 0xffff0000, v242
	v_lshlrev_b32_e32 v252, 16, v243
	v_and_b32_e32 v253, 0xffff0000, v243
	v_pk_fma_f32 v[12:13], v[12:13], v[128:129], v[250:251]
	v_pk_fma_f32 v[14:15], v[14:15], v[130:131], v[252:253]
	v_cvt_pk_bf16_f32 v12, v12, v13
	s_nop 0
	v_cvt_pk_bf16_f32 v13, v14, v15
	global_store_dwordx2 v[158:159], v[12:13], off
	s_waitcnt vmcnt(31)
	v_lshlrev_b32_e32 v250, 16, v244
	v_and_b32_e32 v251, 0xffff0000, v244
	v_lshlrev_b32_e32 v252, 16, v245
	v_and_b32_e32 v253, 0xffff0000, v245
	v_pk_fma_f32 v[8:9], v[8:9], v[132:133], v[250:251]
	v_pk_fma_f32 v[10:11], v[10:11], v[134:135], v[252:253]
	v_cvt_pk_bf16_f32 v8, v8, v9
	s_nop 0
	v_cvt_pk_bf16_f32 v9, v10, v11
	global_store_dwordx2 v[158:159], v[8:9], off offset:32
	s_waitcnt vmcnt(31)
	v_lshlrev_b32_e32 v250, 16, v246
	v_and_b32_e32 v251, 0xffff0000, v246
	v_lshlrev_b32_e32 v252, 16, v247
	v_and_b32_e32 v253, 0xffff0000, v247
	v_pk_fma_f32 v[4:5], v[4:5], v[124:125], v[250:251]
	v_pk_fma_f32 v[6:7], v[6:7], v[126:127], v[252:253]
	v_cvt_pk_bf16_f32 v4, v4, v5
	s_nop 0
	v_cvt_pk_bf16_f32 v5, v6, v7
	global_store_dwordx2 v[158:159], v[4:5], off offset:256
	s_waitcnt vmcnt(31)
	v_lshlrev_b32_e32 v250, 16, v248
	v_and_b32_e32 v251, 0xffff0000, v248
	v_lshlrev_b32_e32 v252, 16, v249
	v_and_b32_e32 v253, 0xffff0000, v249
	v_pk_fma_f32 v[0:1], v[0:1], v[116:117], v[250:251]
	v_pk_fma_f32 v[2:3], v[2:3], v[118:119], v[252:253]
	v_cvt_pk_bf16_f32 v0, v0, v1
	s_nop 0
	v_cvt_pk_bf16_f32 v1, v2, v3
	global_store_dwordx2 v[158:159], v[0:1], off offset:288
	s_cbranch_vccnz .LBB0_1065
	s_andn2_b64 vcc, exec, s[6:7]
	s_cbranch_vccnz .LBB0_1064
	s_barrier
	s_branch .LBB0_1064
